# raw-score row-max extended to the second MLA attention instantiation, on top of k16
# speedup vs baseline: 1.0040x; 1.0040x over previous
; DEV f32x4 mfma16(bf16x8 a, bf16x8 b, f32x4 c) { return __builtin_amdgcn_mfma_f32_16x16x32_bf16(a, b, c, 0, 0, 0); }
; template <int KS>
; DEV void attn_chunk(const unsigned char* Kl, const unsigned char* Vl, const bf16x8 (&qf)[2][KS], f32x4 (&O)[2][4], float (&mrun)[2], float (&lrun)[2],
;                     bool masked, int key0, int qw0, float sl2, int lane, int fr, int fq) {
;     ...
;   for (int kt = 0; kt < 4; ++kt) {
;     sc[0][kt] = (f32x4){0.f, 0.f, 0.f, 0.f}; sc[1][kt] = (f32x4){0.f, 0.f, 0.f, 0.f};
; #pragma unroll
;     for (int kk = 0; kk < KS; ++kk) {
;       bf16x8 kf = *reinterpret_cast<const bf16x8*>(Kl + ((kt * 16 + fr) * KP + kk * 32 + fq * 8) * 2);
;       sc[0][kt] = mfma16(kf, qf[0][kk], sc[0][kt]); sc[1][kt] = mfma16(kf, qf[1][kk], sc[1][kt]);
;     }
;   }
;   bf16x8 pf[2][2];
; #pragma unroll
;   for (int qi = 0; qi < 2; ++qi) {
;     float mx = -1e30f;
; #pragma unroll
;     for (int kt = 0; kt < 4; ++kt)
; #pragma unroll
;       for (int r = 0; r < 4; ++r) { float v = sc[qi][kt][r] * sl2;
;         if (masked) { int kp = key0 + kt * 16 + fq * 4 + r; int dq = qw0 + qi * 16 + fr - kp; if (dq > 128 || dq < -128) v = -1e30f; }
;         sc[qi][kt][r] = v; mx = fmaxf(mx, v); }
;     mx = max_x16_x32(mx);
;     const float mnew = fmaxf(mrun[qi], mx);
;     const float alpha = __builtin_amdgcn_exp2f(mrun[qi] - mnew);
;     mrun[qi] = mnew;
;     float ps = 0.f;
; #pragma unroll
;     for (int kt = 0; kt < 4; ++kt)
; #pragma unroll
;       for (int r = 0; r < 4; ++r) { float pvv = __builtin_amdgcn_exp2f(sc[qi][kt][r] - mnew); ps += pvv; sc[qi][kt][r] = pvv; }
;     pf[qi][0] = pack8(sc[qi][0][0], sc[qi][0][1], sc[qi][0][2], sc[qi][0][3], sc[qi][1][0], sc[qi][1][1], sc[qi][1][2], sc[qi][1][3]);
;     pf[qi][1] = pack8(sc[qi][2][0], sc[qi][2][1], sc[qi][2][2], sc[qi][2][3], sc[qi][3][0], sc[qi][3][1], sc[qi][3][2], sc[qi][3][3]);
;     lrun[qi] = lrun[qi] * alpha + ps;
.LBB0_747:
	ds_read_b128 v[84:87], v0
	ds_read_b128 v[92:95], v0 offset:64
	s_mov_b32 s48, 0xf149f2ca
	s_mov_b32 s8, 0x3e16c740
	s_waitcnt lgkmcnt(1)
	v_mfma_f32_16x16x32_bf16 v[88:91], v[84:87], v[4:7], 0
	ds_read_b128 v[100:103], v0 offset:3392
	ds_read_b128 v[104:107], v0 offset:6720
	ds_read_b128 v[118:121], v0 offset:10048
	v_mfma_f32_16x16x32_bf16 v[84:87], v[84:87], v[20:23], 0
	s_waitcnt lgkmcnt(3)
	v_mfma_f32_16x16x32_bf16 v[88:91], v[92:95], v[8:11], v[88:91]
	v_mfma_f32_16x16x32_bf16 v[84:87], v[92:95], v[16:19], v[84:87]
	ds_read_b128 v[92:95], v0 offset:128
	s_waitcnt lgkmcnt(0)
	v_mfma_f32_16x16x32_bf16 v[88:91], v[92:95], v[12:15], v[88:91]
	v_mfma_f32_16x16x32_bf16 v[92:95], v[92:95], v[24:27], v[84:87]
	s_nop 3
	ds_read_b128 v[84:87], v0 offset:3328
	s_waitcnt lgkmcnt(0)
	v_mfma_f32_16x16x32_bf16 v[96:99], v[84:87], v[4:7], 0
	s_nop 0
	v_mfma_f32_16x16x32_bf16 v[84:87], v[84:87], v[20:23], 0
	v_mfma_f32_16x16x32_bf16 v[96:99], v[100:103], v[8:11], v[96:99]
	v_mfma_f32_16x16x32_bf16 v[84:87], v[100:103], v[16:19], v[84:87]
	ds_read_b128 v[100:103], v0 offset:3456
	s_waitcnt lgkmcnt(0)
	v_mfma_f32_16x16x32_bf16 v[128:131], v[100:103], v[12:15], v[96:99]
	v_mfma_f32_16x16x32_bf16 v[96:99], v[100:103], v[24:27], v[84:87]
	s_nop 3
	ds_read_b128 v[84:87], v0 offset:6656
	s_waitcnt lgkmcnt(0)
	v_mfma_f32_16x16x32_bf16 v[100:103], v[84:87], v[4:7], 0
	v_mfma_f32_16x16x32_bf16 v[84:87], v[84:87], v[20:23], 0
	v_mfma_f32_16x16x32_bf16 v[100:103], v[104:107], v[8:11], v[100:103]
	v_mfma_f32_16x16x32_bf16 v[84:87], v[104:107], v[16:19], v[84:87]
	ds_read_b128 v[104:107], v0 offset:6784
	s_waitcnt lgkmcnt(0)
	v_mfma_f32_16x16x32_bf16 v[136:139], v[104:107], v[12:15], v[100:103]
	v_mfma_f32_16x16x32_bf16 v[100:103], v[104:107], v[24:27], v[84:87]
	s_nop 3
	ds_read_b128 v[84:87], v0 offset:9984
	s_waitcnt lgkmcnt(0)
	v_mfma_f32_16x16x32_bf16 v[104:107], v[84:87], v[4:7], 0
	v_mfma_f32_16x16x32_bf16 v[84:87], v[84:87], v[20:23], 0
	v_mfma_f32_16x16x32_bf16 v[104:107], v[118:121], v[8:11], v[104:107]
	v_mfma_f32_16x16x32_bf16 v[84:87], v[118:121], v[16:19], v[84:87]
	ds_read_b128 v[118:121], v0 offset:10112
	s_waitcnt lgkmcnt(0)
	v_mfma_f32_16x16x32_bf16 v[144:147], v[118:121], v[12:15], v[104:107]
	v_mfma_f32_16x16x32_bf16 v[104:107], v[118:121], v[24:27], v[84:87]
	v_max3_f32 v119, v92, s48, v93
	s_nop 0
	s_nop 5
	v_max3_f32 v84, v88, s48, v89
	v_max3_f32 v84, v84, v90, v91
	v_max3_f32 v84, v84, v128, v129
	v_max3_f32 v84, v84, v130, v131
	v_max3_f32 v84, v84, v136, v137
	v_max3_f32 v84, v84, v138, v139
	v_max3_f32 v84, v84, v144, v145
	v_max3_f32 v84, v84, v146, v147
	v_mul_f32_e32 v84, 0x3e16c740, v84
	v_mov_b32_e32 v85, v84
	v_max3_f32 v119, v119, v94, v95
	s_nop 0
	v_permlane32_swap_b32_e32 v84, v85
	v_max3_f32 v119, v119, v96, v97
	v_max_f32_e32 v85, v85, v85
	v_max_f32_e32 v84, v84, v84
	v_max3_f32 v119, v119, v98, v99
	v_max_f32_e32 v84, v84, v85
	v_max3_f32 v119, v119, v100, v101
	v_mov_b32_e32 v85, v84
	v_max3_f32 v119, v119, v102, v103
	s_nop 0
	v_permlane16_swap_b32_e32 v84, v85
	v_max3_f32 v119, v119, v104, v105
	v_max3_f32 v154, v197, v84, v85
	v_max3_f32 v119, v119, v106, v107
	v_fma_f32 v85, v88, s8, -v154
	v_mul_f32_e32 v119, 0x3e16c740, v119
	v_mov_b32_e32 v121, v119
	v_exp_f32_e32 v118, v85
	v_fma_f32 v85, v89, s8, -v154
	v_permlane32_swap_b32_e32 v119, v121
	v_exp_f32_e32 v122, v85
	v_fma_f32 v85, v90, s8, -v154
	v_max_f32_e32 v121, v121, v121
	v_max_f32_e32 v119, v119, v119
	v_exp_f32_e32 v120, v85
	v_fma_f32 v85, v91, s8, -v154
	v_max_f32_e32 v119, v119, v121
	v_exp_f32_e32 v124, v85
	v_fma_f32 v85, v128, s8, -v154
	v_mov_b32_e32 v121, v119
	v_exp_f32_e32 v128, v85
	v_fma_f32 v85, v129, s8, -v154
	v_permlane16_swap_b32_e32 v119, v121
	v_exp_f32_e32 v126, v85
	v_fma_f32 v85, v130, s8, -v154
	v_max3_f32 v155, v198, v119, v121
	v_exp_f32_e32 v130, v85
	v_fma_f32 v85, v131, s8, -v154
	v_fma_f32 v92, v92, s8, -v155
	v_exp_f32_e32 v134, v85
	v_fma_f32 v85, v136, s8, -v154
	v_exp_f32_e32 v119, v92
	v_fma_f32 v92, v93, s8, -v155
	v_sub_f32_e32 v84, v197, v154
	v_exp_f32_e32 v132, v85
	v_fma_f32 v85, v137, s8, -v154
	v_exp_f32_e32 v123, v92
	v_fma_f32 v92, v94, s8, -v155
	v_exp_f32_e32 v136, v85
	v_fma_f32 v85, v138, s8, -v154
	v_exp_f32_e32 v138, v84
	v_exp_f32_e32 v121, v92
	v_fma_f32 v92, v95, s8, -v155
	v_exp_f32_e32 v125, v92
	v_fma_f32 v92, v96, s8, -v155
	v_exp_f32_e32 v129, v92
	v_fma_f32 v92, v97, s8, -v155
	v_exp_f32_e32 v127, v92
	v_fma_f32 v92, v98, s8, -v155
	v_exp_f32_e32 v142, v85
	v_fma_f32 v85, v139, s8, -v154
	v_pk_mul_f32 v[70:71], v[70:71], v[138:139] op_sel_hi:[1,0]
	v_pk_mul_f32 v[68:69], v[68:69], v[138:139] op_sel_hi:[1,0]
	v_pk_mul_f32 v[74:75], v[74:75], v[138:139] op_sel_hi:[1,0]
	v_pk_mul_f32 v[72:73], v[72:73], v[138:139] op_sel_hi:[1,0]
	v_pk_mul_f32 v[78:79], v[78:79], v[138:139] op_sel_hi:[1,0]
	v_pk_mul_f32 v[76:77], v[76:77], v[138:139] op_sel_hi:[1,0]
	v_pk_mul_f32 v[82:83], v[82:83], v[138:139] op_sel_hi:[1,0]
	v_pk_mul_f32 v[80:81], v[80:81], v[138:139] op_sel_hi:[1,0]
	v_sub_f32_e32 v139, v198, v155
	v_exp_f32_e32 v131, v92
	v_fma_f32 v92, v99, s8, -v155
	v_exp_f32_e32 v135, v92
	v_fma_f32 v92, v100, s8, -v155
	v_exp_f32_e32 v139, v139
	v_exp_f32_e32 v133, v92
	v_fma_f32 v92, v101, s8, -v155
	v_exp_f32_e32 v137, v92
	v_fma_f32 v92, v102, s8, -v155
	v_exp_f32_e32 v143, v92
	v_fma_f32 v92, v103, s8, -v155
	v_exp_f32_e32 v141, v92
	v_fma_f32 v92, v104, s8, -v155
	v_mov_b32_e32 v104, v139
	v_pk_mul_f32 v[54:55], v[54:55], v[104:105] op_sel_hi:[1,0]
	v_pk_mul_f32 v[52:53], v[52:53], v[104:105] op_sel_hi:[1,0]
	v_pk_mul_f32 v[58:59], v[58:59], v[104:105] op_sel_hi:[1,0]
	v_pk_mul_f32 v[56:57], v[56:57], v[104:105] op_sel_hi:[1,0]
	v_pk_mul_f32 v[102:103], v[66:67], v[104:105] op_sel_hi:[1,0]
	v_pk_mul_f32 v[100:101], v[64:65], v[104:105] op_sel_hi:[1,0]
	v_pk_mul_f32 v[66:67], v[62:63], v[104:105] op_sel_hi:[1,0]
	v_pk_mul_f32 v[64:65], v[60:61], v[104:105] op_sel_hi:[1,0]
	v_add_u32_e32 v104, 0x6800, v3
	ds_read2_b64 v[60:63], v104 offset1:4
	v_cvt_pk_bf16_f32 v88, v118, v122
	v_cvt_pk_bf16_f32 v89, v120, v124
	v_cvt_pk_bf16_f32 v90, v128, v126
	v_cvt_pk_bf16_f32 v91, v130, v134
	v_cvt_pk_bf16_f32 v96, v119, v123
	v_cvt_pk_bf16_f32 v97, v121, v125
	v_cvt_pk_bf16_f32 v98, v129, v127
	v_cvt_pk_bf16_f32 v99, v131, v135
	v_exp_f32_e32 v140, v85
	v_fma_f32 v85, v144, s8, -v154
	s_waitcnt lgkmcnt(0)
; DEV f32x4 mfma16(bf16x8 a, bf16x8 b, f32x4 c) { return __builtin_amdgcn_mfma_f32_16x16x32_bf16(a, b, c, 0, 0, 0); }
; template <int KS>
; DEV void attn_chunk(const unsigned char* Kl, const unsigned char* Vl, const bf16x8 (&qf)[2][KS], f32x4 (&O)[2][4], float (&mrun)[2], float (&lrun)[2],
;                     bool masked, int key0, int qw0, float sl2, int lane, int fr, int fq) {
;     ...
; #pragma unroll
;   for (int dt = 0; dt < 4; ++dt)
; #pragma unroll
;     for (int sub = 0; sub < 2; ++sub) {
;       const unsigned char* vp = Vl + ((dt * 16 + fr) * VP + sub * 32 + fq * 4) * 2;
;       u32x2 v0 = *reinterpret_cast<const u32x2*>(vp), v1 = *reinterpret_cast<const u32x2*>(vp + 32);
;       u32x4 vv = {v0[0], v0[1], v1[0], v1[1]};
;       bf16x8 vf = *reinterpret_cast<bf16x8*>(&vv);
;       O[0][dt] = mfma16(vf, pf[0][sub], O[0][dt]); O[1][dt] = mfma16(vf, pf[1][sub], O[1][dt]);
;     }
	v_mfma_f32_16x16x32_bf16 v[68:71], v[60:63], v[88:91], v[68:71]
	v_exp_f32_e32 v150, v85
	v_fma_f32 v85, v145, s8, -v154
	v_exp_f32_e32 v151, v92
	v_mfma_f32_16x16x32_bf16 v[52:55], v[60:63], v[96:99], v[52:55]
	ds_read2_b64 v[60:63], v104 offset0:8 offset1:12
	v_fma_f32 v92, v105, s8, -v155
	v_exp_f32_e32 v148, v85
	v_fma_f32 v85, v146, s8, -v154
	v_exp_f32_e32 v149, v92
	v_fma_f32 v92, v106, s8, -v155
	v_exp_f32_e32 v146, v85
	v_fma_f32 v85, v147, s8, -v154
	v_exp_f32_e32 v147, v92
	v_fma_f32 v92, v107, s8, -v155
	v_exp_f32_e32 v144, v85
	v_exp_f32_e32 v145, v92
	v_cvt_pk_bf16_f32 v84, v132, v136
	v_cvt_pk_bf16_f32 v85, v142, v140
	v_cvt_pk_bf16_f32 v86, v150, v148
	v_cvt_pk_bf16_f32 v87, v146, v144
	v_cvt_pk_bf16_f32 v92, v133, v137
	v_cvt_pk_bf16_f32 v93, v143, v141
	v_cvt_pk_bf16_f32 v94, v151, v149
	v_cvt_pk_bf16_f32 v95, v147, v145
	v_add_u32_e32 v104, 0x7000, v3
	s_waitcnt lgkmcnt(0)
	v_mfma_f32_16x16x32_bf16 v[68:71], v[60:63], v[84:87], v[68:71]
	v_mfma_f32_16x16x32_bf16 v[52:55], v[60:63], v[92:95], v[52:55]
	ds_read2_b64 v[60:63], v104 offset0:32 offset1:36
	s_waitcnt lgkmcnt(0)
	v_mfma_f32_16x16x32_bf16 v[72:75], v[60:63], v[88:91], v[72:75]
	v_mfma_f32_16x16x32_bf16 v[56:59], v[60:63], v[96:99], v[56:59]
	ds_read2_b64 v[60:63], v104 offset0:40 offset1:44
	v_add_u32_e32 v104, 0x7800, v3
	s_waitcnt lgkmcnt(0)
	v_mfma_f32_16x16x32_bf16 v[72:75], v[60:63], v[84:87], v[72:75]
	v_mfma_f32_16x16x32_bf16 v[56:59], v[60:63], v[92:95], v[56:59]
	ds_read2_b64 v[60:63], v104 offset0:64 offset1:68
	s_waitcnt lgkmcnt(0)
	v_mfma_f32_16x16x32_bf16 v[76:79], v[60:63], v[88:91], v[76:79]
	v_mfma_f32_16x16x32_bf16 v[60:63], v[60:63], v[96:99], v[100:103]
	s_nop 2
	ds_read2_b64 v[100:103], v104 offset0:72 offset1:76
	v_add_u32_e32 v104, 0x8000, v3
	s_waitcnt lgkmcnt(0)
	v_mfma_f32_16x16x32_bf16 v[76:79], v[100:103], v[84:87], v[76:79]
	v_mfma_f32_16x16x32_bf16 v[60:63], v[100:103], v[92:95], v[60:63]
	ds_read2_b64 v[100:103], v104 offset0:96 offset1:100
	s_waitcnt lgkmcnt(0)
	v_mfma_f32_16x16x32_bf16 v[80:83], v[100:103], v[88:91], v[80:83]
	ds_read2_b64 v[88:91], v104 offset0:104 offset1:108
	s_waitcnt vmcnt(1)
	ds_write_b128 v194, v[36:39] offset:13312
	v_mfma_f32_16x16x32_bf16 v[64:67], v[100:103], v[96:99], v[64:67]
	s_waitcnt lgkmcnt(1)
	v_mfma_f32_16x16x32_bf16 v[84:87], v[88:91], v[84:87], v[80:83]
	v_mfma_f32_16x16x32_bf16 v[64:67], v[88:91], v[92:95], v[64:67]
	s_and_saveexec_b64 s[48:49], s[40:41]
	ds_write_b128 v195, v[44:47] offset:13312
	s_or_b64 exec, exec, s[48:49]
	s_waitcnt vmcnt(0)
	ds_write_b128 v196, v[48:51] offset:35840
	s_waitcnt lgkmcnt(0)
	s_barrier
	s_cmp_gt_u32 s50, 32
	s_cbranch_scc1 .LBB0_753
	v_add_co_u32_e32 v36, vcc, 0x1e6ad000, v152
	s_nop 1
	v_addc_co_u32_e32 v37, vcc, 0, v153, vcc
	global_load_dwordx4 v[36:39], v[36:37], off
	s_and_saveexec_b64 s[48:49], s[40:41]
	s_cbranch_execz .LBB0_752
	v_lshl_add_u64 v[44:45], s[88:89], 0, v[114:115]
	v_add_co_u32_e32 v44, vcc, 0x1e6ad000, v44
	s_nop 1
	v_addc_co_u32_e32 v45, vcc, 0, v45, vcc
	global_load_dwordx4 v[44:47], v[44:45], off

; DEV f32x4 mfma16(bf16x8 a, bf16x8 b, f32x4 c) { return __builtin_amdgcn_mfma_f32_16x16x32_bf16(a, b, c, 0, 0, 0); }
; template <int KS>
; DEV void attn_chunk(const unsigned char* Kl, const unsigned char* Vl, const bf16x8 (&qf)[2][KS], f32x4 (&O)[2][4], float (&mrun)[2], float (&lrun)[2],
;                     bool masked, int key0, int qw0, float sl2, int lane, int fr, int fq) {
;     ...
;   for (int kt = 0; kt < 4; ++kt) {
;     sc[0][kt] = (f32x4){0.f, 0.f, 0.f, 0.f}; sc[1][kt] = (f32x4){0.f, 0.f, 0.f, 0.f};
; #pragma unroll
;     for (int kk = 0; kk < KS; ++kk) {
;       bf16x8 kf = *reinterpret_cast<const bf16x8*>(Kl + ((kt * 16 + fr) * KP + kk * 32 + fq * 8) * 2);
;       sc[0][kt] = mfma16(kf, qf[0][kk], sc[0][kt]); sc[1][kt] = mfma16(kf, qf[1][kk], sc[1][kt]);
;     }
;   }
;   bf16x8 pf[2][2];
; #pragma unroll
;   for (int qi = 0; qi < 2; ++qi) {
;     float mx = -1e30f;
; #pragma unroll
;     for (int kt = 0; kt < 4; ++kt)
; #pragma unroll
;       for (int r = 0; r < 4; ++r) { float v = sc[qi][kt][r] * sl2;
;         if (masked) { int kp = key0 + kt * 16 + fq * 4 + r; int dq = qw0 + qi * 16 + fr - kp; if (dq > 128 || dq < -128) v = -1e30f; }
;         sc[qi][kt][r] = v; mx = fmaxf(mx, v); }
;     mx = max_x16_x32(mx);
;     const float mnew = fmaxf(mrun[qi], mx);
;     const float alpha = __builtin_amdgcn_exp2f(mrun[qi] - mnew);
;     mrun[qi] = mnew;
;     float ps = 0.f;
; #pragma unroll
;     for (int kt = 0; kt < 4; ++kt)
; #pragma unroll
;       for (int r = 0; r < 4; ++r) { float pvv = __builtin_amdgcn_exp2f(sc[qi][kt][r] - mnew); ps += pvv; sc[qi][kt][r] = pvv; }
;     pf[qi][0] = pack8(sc[qi][0][0], sc[qi][0][1], sc[qi][0][2], sc[qi][0][3], sc[qi][1][0], sc[qi][1][1], sc[qi][1][2], sc[qi][1][3]);
;     pf[qi][1] = pack8(sc[qi][2][0], sc[qi][2][1], sc[qi][2][2], sc[qi][2][3], sc[qi][3][0], sc[qi][3][1], sc[qi][3][2], sc[qi][3][3]);
;     lrun[qi] = lrun[qi] * alpha + ps;
.LBB0_753:
	ds_read_b128 v[80:83], v0 offset:13312
	ds_read_b128 v[92:95], v0 offset:13376
	s_mov_b32 s48, 0xf149f2ca
	s_andn2_b64 vcc, exec, s[44:45]
	s_waitcnt lgkmcnt(1)
	v_mfma_f32_16x16x32_bf16 v[88:91], v[80:83], v[4:7], 0
	ds_read_b128 v[100:103], v0 offset:16704
	ds_read_b128 v[104:107], v0 offset:20032
	ds_read_b128 v[156:159], v0 offset:23360
	v_mfma_f32_16x16x32_bf16 v[80:83], v[80:83], v[20:23], 0
	s_waitcnt lgkmcnt(3)
	v_mfma_f32_16x16x32_bf16 v[88:91], v[92:95], v[8:11], v[88:91]
	v_mfma_f32_16x16x32_bf16 v[80:83], v[92:95], v[16:19], v[80:83]
	ds_read_b128 v[92:95], v0 offset:13440
	s_waitcnt lgkmcnt(0)
	v_mfma_f32_16x16x32_bf16 v[88:91], v[92:95], v[12:15], v[88:91]
	v_mfma_f32_16x16x32_bf16 v[92:95], v[92:95], v[24:27], v[80:83]
	s_nop 3
	ds_read_b128 v[80:83], v0 offset:16640
	s_waitcnt lgkmcnt(0)
	v_mfma_f32_16x16x32_bf16 v[96:99], v[80:83], v[4:7], 0
	s_nop 0
	v_mfma_f32_16x16x32_bf16 v[80:83], v[80:83], v[20:23], 0
	v_mfma_f32_16x16x32_bf16 v[96:99], v[100:103], v[8:11], v[96:99]
	v_mfma_f32_16x16x32_bf16 v[80:83], v[100:103], v[16:19], v[80:83]
	ds_read_b128 v[100:103], v0 offset:16768
	s_waitcnt lgkmcnt(0)
	v_mfma_f32_16x16x32_bf16 v[162:165], v[100:103], v[12:15], v[96:99]
	v_mfma_f32_16x16x32_bf16 v[96:99], v[100:103], v[24:27], v[80:83]
	s_nop 3
	ds_read_b128 v[80:83], v0 offset:19968
	s_waitcnt lgkmcnt(0)
	v_mfma_f32_16x16x32_bf16 v[100:103], v[80:83], v[4:7], 0
	v_mfma_f32_16x16x32_bf16 v[80:83], v[80:83], v[20:23], 0
	v_mfma_f32_16x16x32_bf16 v[100:103], v[104:107], v[8:11], v[100:103]
	v_mfma_f32_16x16x32_bf16 v[80:83], v[104:107], v[16:19], v[80:83]
	ds_read_b128 v[104:107], v0 offset:20096
	s_waitcnt lgkmcnt(0)
	v_mfma_f32_16x16x32_bf16 v[170:173], v[104:107], v[12:15], v[100:103]
	v_mfma_f32_16x16x32_bf16 v[100:103], v[104:107], v[24:27], v[80:83]
	s_nop 3
	ds_read_b128 v[80:83], v0 offset:23296
	s_waitcnt lgkmcnt(0)
	v_mfma_f32_16x16x32_bf16 v[104:107], v[80:83], v[4:7], 0
	v_mfma_f32_16x16x32_bf16 v[80:83], v[80:83], v[20:23], 0
	v_mfma_f32_16x16x32_bf16 v[104:107], v[156:159], v[8:11], v[104:107]
	v_mfma_f32_16x16x32_bf16 v[80:83], v[156:159], v[16:19], v[80:83]
	ds_read_b128 v[156:159], v0 offset:23424
	s_waitcnt lgkmcnt(0)
	v_mfma_f32_16x16x32_bf16 v[184:187], v[156:159], v[12:15], v[104:107]
	v_mfma_f32_16x16x32_bf16 v[104:107], v[156:159], v[24:27], v[80:83]
	v_max3_f32 v153, v92, s48, v93
	s_nop 0
	s_nop 5
	v_max3_f32 v80, v88, s48, v89
	v_max3_f32 v80, v80, v90, v91
	v_max3_f32 v80, v80, v162, v163
	v_max3_f32 v80, v80, v164, v165
	v_max3_f32 v80, v80, v170, v171
	v_max3_f32 v80, v80, v172, v173
	v_max3_f32 v80, v80, v184, v185
	v_max3_f32 v80, v80, v186, v187
	v_mul_f32_e32 v80, 0x3e16c740, v80
	v_mov_b32_e32 v81, v80
	s_nop 1
	v_permlane32_swap_b32_e32 v80, v81
	v_max_f32_e32 v81, v81, v81
	v_max_f32_e32 v80, v80, v80
	v_max_f32_e32 v80, v80, v81
	v_mov_b32_e32 v81, v80
	v_max3_f32 v153, v153, v94, v95
	s_nop 0
	v_permlane16_swap_b32_e32 v80, v81
	v_max3_f32 v153, v153, v96, v97
	v_max3_f32 v197, v154, v80, v81
	v_max3_f32 v153, v153, v98, v99
	v_fma_f32 v81, v88, s8, -v197
	v_max3_f32 v153, v153, v100, v101
	v_exp_f32_e32 v152, v81
	v_fma_f32 v81, v89, s8, -v197
	v_max3_f32 v153, v153, v102, v103
	v_exp_f32_e32 v156, v81
	v_fma_f32 v81, v90, s8, -v197
	v_max3_f32 v153, v153, v104, v105
	v_sub_f32_e32 v80, v154, v197
	v_exp_f32_e32 v154, v81
	v_fma_f32 v81, v91, s8, -v197
	v_max3_f32 v153, v153, v106, v107
	v_exp_f32_e32 v158, v81
	v_fma_f32 v81, v162, s8, -v197
	v_mul_f32_e32 v153, 0x3e16c740, v153
	v_mov_b32_e32 v157, v153
	v_exp_f32_e32 v162, v81
	v_fma_f32 v81, v163, s8, -v197
	v_permlane32_swap_b32_e32 v153, v157
	v_exp_f32_e32 v160, v81
	v_fma_f32 v81, v164, s8, -v197
	v_max_f32_e32 v157, v157, v157
	v_max_f32_e32 v153, v153, v153
	v_exp_f32_e32 v164, v81
	v_fma_f32 v81, v165, s8, -v197
	v_max_f32_e32 v153, v153, v157
	v_exp_f32_e32 v168, v81
	v_fma_f32 v81, v170, s8, -v197
	v_mov_b32_e32 v157, v153
	v_exp_f32_e32 v166, v81
	v_fma_f32 v81, v171, s8, -v197
	v_permlane16_swap_b32_e32 v153, v157
	v_exp_f32_e32 v170, v81
	v_fma_f32 v81, v172, s8, -v197
	v_exp_f32_e32 v172, v80
	v_max3_f32 v198, v155, v153, v157
	v_fma_f32 v92, v92, s8, -v198
	v_exp_f32_e32 v153, v92
	v_fma_f32 v92, v93, s8, -v198
	v_exp_f32_e32 v157, v92
	v_fma_f32 v92, v94, s8, -v198
	v_exp_f32_e32 v176, v81
	v_fma_f32 v81, v173, s8, -v197
	v_pk_mul_f32 v[70:71], v[70:71], v[172:173] op_sel_hi:[1,0]
	v_pk_mul_f32 v[68:69], v[68:69], v[172:173] op_sel_hi:[1,0]
	v_pk_mul_f32 v[74:75], v[74:75], v[172:173] op_sel_hi:[1,0]
	v_pk_mul_f32 v[72:73], v[72:73], v[172:173] op_sel_hi:[1,0]
	v_pk_mul_f32 v[78:79], v[78:79], v[172:173] op_sel_hi:[1,0]
	v_pk_mul_f32 v[76:77], v[76:77], v[172:173] op_sel_hi:[1,0]
	v_pk_mul_f32 v[86:87], v[86:87], v[172:173] op_sel_hi:[1,0]
	v_pk_mul_f32 v[84:85], v[84:85], v[172:173] op_sel_hi:[1,0]
	v_sub_f32_e32 v173, v155, v198
	v_exp_f32_e32 v155, v92
	v_fma_f32 v92, v95, s8, -v198
	v_exp_f32_e32 v159, v92
	v_fma_f32 v92, v96, s8, -v198
	v_exp_f32_e32 v163, v92
	v_fma_f32 v92, v97, s8, -v198
	v_exp_f32_e32 v161, v92
	v_fma_f32 v92, v98, s8, -v198
	v_exp_f32_e32 v165, v92
	v_fma_f32 v92, v99, s8, -v198
	v_exp_f32_e32 v169, v92
	v_fma_f32 v92, v100, s8, -v198
	v_exp_f32_e32 v173, v173
	v_exp_f32_e32 v167, v92
	v_fma_f32 v92, v101, s8, -v198
	v_exp_f32_e32 v171, v92
	v_fma_f32 v92, v102, s8, -v198
	v_exp_f32_e32 v177, v92
	v_fma_f32 v92, v103, s8, -v198
	v_exp_f32_e32 v175, v92
	v_fma_f32 v92, v104, s8, -v198
	v_mov_b32_e32 v104, v173
	v_pk_mul_f32 v[54:55], v[54:55], v[104:105] op_sel_hi:[1,0]
	v_pk_mul_f32 v[52:53], v[52:53], v[104:105] op_sel_hi:[1,0]
	v_pk_mul_f32 v[58:59], v[58:59], v[104:105] op_sel_hi:[1,0]
	v_pk_mul_f32 v[56:57], v[56:57], v[104:105] op_sel_hi:[1,0]
	v_pk_mul_f32 v[102:103], v[62:63], v[104:105] op_sel_hi:[1,0]
	v_pk_mul_f32 v[100:101], v[60:61], v[104:105] op_sel_hi:[1,0]
	v_pk_mul_f32 v[62:63], v[66:67], v[104:105] op_sel_hi:[1,0]
	v_pk_mul_f32 v[60:61], v[64:65], v[104:105] op_sel_hi:[1,0]
	v_add_u32_e32 v104, 0x8800, v3
	ds_read2_b64 v[64:67], v104 offset0:128 offset1:132
	v_cvt_pk_bf16_f32 v88, v152, v156
	v_cvt_pk_bf16_f32 v89, v154, v158
	v_cvt_pk_bf16_f32 v90, v162, v160
	v_cvt_pk_bf16_f32 v91, v164, v168
	v_cvt_pk_bf16_f32 v96, v153, v157
	v_cvt_pk_bf16_f32 v97, v155, v159
	v_cvt_pk_bf16_f32 v98, v163, v161
	v_cvt_pk_bf16_f32 v99, v165, v169
	v_exp_f32_e32 v174, v81
	v_fma_f32 v81, v184, s8, -v197
	s_waitcnt lgkmcnt(0)
; DEV f32x4 mfma16(bf16x8 a, bf16x8 b, f32x4 c) { return __builtin_amdgcn_mfma_f32_16x16x32_bf16(a, b, c, 0, 0, 0); }
; #define LOADSET(r0_, r1_, rv_, i_) do { const int kn_ = CH_OF(i_) * 64; \
;     r0_ = ldg8(Kb + (size_t)(kn_ + kr0) * DK + kc0 * 8); if (has1) r1_ = ldg8(Kb + (size_t)(kn_ + kr1) * DK + kc1 * 8); \
;     rv_ = ldg8(Vt + (size_t)vd * NKEY + kn_ + vpart * 8); } while (0)
; #define STORESET(r0_, r1_, rv_, i_) do { unsigned char* kb_ = smem + ((i_) & 1) * KBYTES; \
;     *reinterpret_cast<bf16x8*>(kb_ + koff0) = r0_; if (has1) *reinterpret_cast<bf16x8*>(kb_ + koff1) = r1_; \
;     *reinterpret_cast<bf16x8*>(smem + voff + ((i_) & 1) * VBYTES) = rv_; } while (0)
; template <int KS>
; DEV void attn_chunk(const unsigned char* Kl, const unsigned char* Vl, const bf16x8 (&qf)[2][KS], f32x4 (&O)[2][4], float (&mrun)[2], float (&lrun)[2],
;                     bool masked, int key0, int qw0, float sl2, int lane, int fr, int fq) {
;     ...
; #pragma unroll
;   for (int dt = 0; dt < 4; ++dt)
; #pragma unroll
;     for (int sub = 0; sub < 2; ++sub) {
;       const unsigned char* vp = Vl + ((dt * 16 + fr) * VP + sub * 32 + fq * 4) * 2;
;       u32x2 v0 = *reinterpret_cast<const u32x2*>(vp), v1 = *reinterpret_cast<const u32x2*>(vp + 32);
;       u32x4 vv = {v0[0], v0[1], v1[0], v1[1]};
;       bf16x8 vf = *reinterpret_cast<bf16x8*>(&vv);
;       O[0][dt] = mfma16(vf, pf[0][sub], O[0][dt]); O[1][dt] = mfma16(vf, pf[1][sub], O[1][dt]);
;     }
; template <int KS>
; DEV void attn_block(const bf16* Q, int ldq, const bf16* Kb, const bf16* Vt, int a_lo, int a_hi, int b_lo, int b_hi, bool maskA, int qpos_blk,
;                     float scale, bool has_sink, float sink, bf16* out, int ldo) {
;     ...
;   LOADSET(a0, a1, av, 0);
;   STORESET(a0, a1, av, 0);
;   if (n > 1) LOADSET(b0, b1, bv, 1);
;   __syncthreads();
; #pragma unroll 1
;   for (int it = 0; it < n; it += 2) {
;     BODY(it, a0, a1, av, b0, b1, bv);
;     if (it + 1 < n) BODY(it + 1, b0, b1, bv, a0, a1, av);
	v_mfma_f32_16x16x32_bf16 v[68:71], v[64:67], v[88:91], v[68:71]
	v_exp_f32_e32 v190, v81
	v_fma_f32 v81, v185, s8, -v197
	v_exp_f32_e32 v191, v92
	v_mfma_f32_16x16x32_bf16 v[52:55], v[64:67], v[96:99], v[52:55]
	ds_read2_b64 v[64:67], v104 offset0:136 offset1:140
	v_fma_f32 v92, v105, s8, -v198
	v_exp_f32_e32 v188, v81
	v_fma_f32 v81, v186, s8, -v197
	v_exp_f32_e32 v189, v92
	v_fma_f32 v92, v106, s8, -v198
	v_exp_f32_e32 v186, v81
	v_fma_f32 v81, v187, s8, -v197
	v_exp_f32_e32 v187, v92
	v_fma_f32 v92, v107, s8, -v198
	v_exp_f32_e32 v184, v81
	v_exp_f32_e32 v185, v92
	v_cvt_pk_bf16_f32 v80, v166, v170
	v_cvt_pk_bf16_f32 v81, v176, v174
	v_cvt_pk_bf16_f32 v82, v190, v188
	v_cvt_pk_bf16_f32 v83, v186, v184
	v_cvt_pk_bf16_f32 v92, v167, v171
	v_cvt_pk_bf16_f32 v93, v177, v175
	v_cvt_pk_bf16_f32 v94, v191, v189
	v_cvt_pk_bf16_f32 v95, v187, v185
	v_add_u32_e32 v104, 0x9000, v3
	s_waitcnt lgkmcnt(0)
	v_mfma_f32_16x16x32_bf16 v[68:71], v[64:67], v[80:83], v[68:71]
	v_mfma_f32_16x16x32_bf16 v[52:55], v[64:67], v[92:95], v[52:55]
	ds_read2_b64 v[64:67], v104 offset0:160 offset1:164
	s_waitcnt lgkmcnt(0)
	v_mfma_f32_16x16x32_bf16 v[72:75], v[64:67], v[88:91], v[72:75]
	v_mfma_f32_16x16x32_bf16 v[56:59], v[64:67], v[96:99], v[56:59]
	ds_read2_b64 v[64:67], v104 offset0:168 offset1:172
	v_add_u32_e32 v104, 0x9800, v3
	s_waitcnt lgkmcnt(0)
	v_mfma_f32_16x16x32_bf16 v[72:75], v[64:67], v[80:83], v[72:75]
	v_mfma_f32_16x16x32_bf16 v[56:59], v[64:67], v[92:95], v[56:59]
	ds_read2_b64 v[64:67], v104 offset0:192 offset1:196
	s_waitcnt lgkmcnt(0)
	v_mfma_f32_16x16x32_bf16 v[76:79], v[64:67], v[88:91], v[76:79]
	v_mfma_f32_16x16x32_bf16 v[64:67], v[64:67], v[96:99], v[100:103]
	s_nop 2
	ds_read2_b64 v[100:103], v104 offset0:200 offset1:204
	v_add_u32_e32 v104, 0xa000, v3
	s_waitcnt lgkmcnt(0)
	v_mfma_f32_16x16x32_bf16 v[76:79], v[100:103], v[80:83], v[76:79]
	v_mfma_f32_16x16x32_bf16 v[64:67], v[100:103], v[92:95], v[64:67]
	ds_read2_b64 v[100:103], v104 offset0:224 offset1:228
	s_waitcnt lgkmcnt(0)
	v_mfma_f32_16x16x32_bf16 v[84:87], v[100:103], v[88:91], v[84:87]
	ds_read2_b64 v[88:91], v104 offset0:232 offset1:236
	v_mfma_f32_16x16x32_bf16 v[60:63], v[100:103], v[96:99], v[60:63]
	s_waitcnt lgkmcnt(0)
	v_mfma_f32_16x16x32_bf16 v[80:83], v[88:91], v[80:83], v[84:87]
	v_mfma_f32_16x16x32_bf16 v[60:63], v[88:91], v[92:95], v[60:63]
	s_cbranch_vccnz .LBB0_742
	ds_write_b128 v194, v[28:31]
	s_and_saveexec_b64 s[44:45], s[40:41]
	s_cbranch_execz .LBB0_741
	ds_write_b128 v195, v[32:35]
	s_branch .LBB0_741
